# GEMM K loop: dropped the second lgkmcnt(0) after the barrier (the identical wait before the barrier already covers every ds_read; no LDS op in between)
# baseline (speedup 1.0000x reference)
; #define PG8_STAGE(bufoff, gbase, voff) do { _Pragma("unroll") for (int _i = 0; _i < 2; ++_i) \
;         __builtin_amdgcn_global_load_lds((const unsigned*)((const char*)(gbase) + (voff)[_i]), (PG8_LAS unsigned*)(lds + (bufoff) + ldsw + _i * 8192), 16, 0, 0); } while (0)
; #define PG8_LDA(dst, b, h) do { _Pragma("unroll") for (int m = 0; m < 4; ++m) _Pragma("unroll") for (int k = 0; k < 2; ++k) dst[m][k] = *(const PG8_LAS bf16x8*)(lds + PG8_SA(b, h) + aoff + m * 2048 + k * 1024); } while (0)
; #define PG8_LDB(dst, b, h) do { _Pragma("unroll") for (int n = 0; n < 2; ++n) _Pragma("unroll") for (int k = 0; k < 2; ++k) dst[n][k] = *(const PG8_LAS bf16x8*)(lds + PG8_SB(b, h) + boff + n * 2048 + k * 1024); } while (0)
; #define PG8_WAIT_V(n) asm volatile("s_waitcnt vmcnt(" #n ")" ::: "memory")
; #define PG8_WAIT_L(n) asm volatile("s_waitcnt lgkmcnt(" #n ")" ::: "memory")
; #define PG8_BAR __builtin_amdgcn_s_barrier()
; #define PG8_SCHED __builtin_amdgcn_sched_barrier(0)
; template <class Epi, class Sched, bool ALIGN_EPI = false, bool SP2 = false>
; __device__ __forceinline__ void gemm_phase(PG8_LAS unsigned char* lds, const Gemm g, const Sched& S, const Epi& E) {
;     ...
;         const char* nA = has_next ? (const char*)g.A + (size_t)nxt.pm * tstep : cA; const char* nB = has_next ? (const char*)g.Bt + (size_t)nxt.pn * tstep : cB;
;         for (int t = 0; t < nt; t += 2) {
;             const bool last = (t == nt - 2);
;             const char* a1 = cA + (size_t)(t + 1) * kstep;
;             const char* a2 = last ? nA : cA + (size_t)(t + 2) * kstep; const char* b2 = last ? nB : cB + (size_t)(t + 2) * kstep;
;             const char* a3 = a2 + kstep; const char* b3 = b2 + kstep;
;             if (last && has_next) S.a_ready(nxt);
;             if constexpr (SP2) {
;             PG8_LDB(B0, 0, 0); PG8_LDB(B1, 0, 1); PG8_SCHED; PG8_LDA(At, 0, 0); PG8_STAGE(PG8_SA(1, 1), a1 + hstep, voffA);
;             PG8_WAIT_V(8); PG8_WAIT_L(0); PG8_BAR; PG8_MMA(0, 0, At, B0); PG8_MMA(0, 1, At, B1); PG8_BAR; PG8_SCHED;
;             PG8_LDA(At, 0, 1); PG8_STAGE(PG8_SB(0, 0), b2, voffB); PG8_STAGE(PG8_SB(0, 1), b2 + hstep, voffB); PG8_STAGE(PG8_SA(0, 0), a2, voffA);
;             PG8_WAIT_V(8); PG8_WAIT_L(0); PG8_BAR; PG8_MMA(1, 0, At, B0); PG8_MMA(1, 1, At, B1); PG8_BAR; PG8_SCHED;
.LBB0_321:
	s_add_u32 s12, s16, 0x80
	s_addc_u32 s13, s17, 0
	s_add_u32 s16, s14, 0x100
	s_addc_u32 s17, s15, 0
	s_mov_b32 s14, 0
	s_nop 0
	s_nop 0
	s_waitcnt lgkmcnt(0)
	s_add_i32 s42, s14, 2
	s_add_u32 s43, s12, 0x80
	s_addc_u32 s15, s13, 0
	s_add_i32 s75, 0, 0x10000
	s_cmp_eq_u32 s25, s14
	s_cselect_b32 s15, s55, s15
	s_cselect_b32 s14, s54, s43
	s_cselect_b32 vcc_hi, s65, s17
	s_cselect_b32 vcc_lo, s64, s16
	s_add_i32 s43, 0, 0x14000
	v_add_u32_e32 v142, s75, v199
	v_add_u32_e32 v178, s43, v199
	ds_read_b128 v[130:133], v142
	ds_read_b128 v[134:137], v142 offset:1024
	ds_read_b128 v[138:141], v142 offset:2048
	ds_read_b128 v[142:145], v142 offset:3072
	ds_read_b128 v[170:173], v178
	ds_read_b128 v[174:177], v178 offset:1024
	ds_read_b128 v[202:205], v178 offset:2048
	ds_read_b128 v[206:209], v178 offset:3072
	v_lshl_add_u64 v[178:179], s[12:13], 0, v[166:167]
	s_add_i32 m0, s56, 0xc000
	ds_read_b128 v[210:213], v201
	ds_read_b128 v[214:217], v201 offset:1024
	ds_read_b128 v[218:221], v201 offset:2048
	ds_read_b128 v[222:225], v201 offset:3072
	ds_read_b128 v[226:229], v201 offset:4096
	ds_read_b128 v[230:233], v201 offset:5120
	ds_read_b128 v[234:237], v201 offset:6144
	ds_read_b128 v[238:241], v201 offset:7168
	global_load_lds_dwordx4 v[178:179], off
	v_lshl_add_u64 v[178:179], s[12:13], 0, v[168:169]
	s_add_i32 m0, s56, 0xe000
	s_nop 0
	global_load_lds_dwordx4 v[178:179], off
	s_waitcnt vmcnt(8)
	s_waitcnt lgkmcnt(0)
	s_barrier
	s_setprio 1
	v_mfma_f32_16x16x32_bf16 v[126:129], v[130:133], v[210:213], 0
	v_mfma_f32_16x16x32_bf16 v[126:129], v[134:137], v[214:217], v[126:129]
	v_mfma_f32_16x16x32_bf16 v[122:125], v[138:141], v[210:213], 0
	v_mfma_f32_16x16x32_bf16 v[122:125], v[142:145], v[214:217], v[122:125]
	v_mfma_f32_16x16x32_bf16 v[110:113], v[130:133], v[218:221], 0
	v_mfma_f32_16x16x32_bf16 v[110:113], v[134:137], v[222:225], v[110:113]
	v_mfma_f32_16x16x32_bf16 v[106:109], v[138:141], v[218:221], 0
	v_mfma_f32_16x16x32_bf16 v[106:109], v[142:145], v[222:225], v[106:109]
	v_mfma_f32_16x16x32_bf16 v[94:97], v[130:133], v[226:229], 0
	v_mfma_f32_16x16x32_bf16 v[94:97], v[134:137], v[230:233], v[94:97]
	v_mfma_f32_16x16x32_bf16 v[90:93], v[138:141], v[226:229], 0
	v_mfma_f32_16x16x32_bf16 v[90:93], v[142:145], v[230:233], v[90:93]
	v_mfma_f32_16x16x32_bf16 v[78:81], v[130:133], v[234:237], 0
	v_mfma_f32_16x16x32_bf16 v[78:81], v[134:137], v[238:241], v[78:81]
	v_mfma_f32_16x16x32_bf16 v[74:77], v[138:141], v[234:237], 0
	v_mfma_f32_16x16x32_bf16 v[74:77], v[142:145], v[238:241], v[74:77]
	v_mfma_f32_16x16x32_bf16 v[118:121], v[170:173], v[210:213], 0
	v_mfma_f32_16x16x32_bf16 v[118:121], v[174:177], v[214:217], v[118:121]
	v_mfma_f32_16x16x32_bf16 v[114:117], v[202:205], v[210:213], 0
	v_mfma_f32_16x16x32_bf16 v[114:117], v[206:209], v[214:217], v[114:117]
	v_mfma_f32_16x16x32_bf16 v[102:105], v[170:173], v[218:221], 0
	v_mfma_f32_16x16x32_bf16 v[102:105], v[174:177], v[222:225], v[102:105]
	v_mfma_f32_16x16x32_bf16 v[98:101], v[202:205], v[218:221], 0
	v_mfma_f32_16x16x32_bf16 v[98:101], v[206:209], v[222:225], v[98:101]
	v_mfma_f32_16x16x32_bf16 v[86:89], v[170:173], v[226:229], 0
	v_mfma_f32_16x16x32_bf16 v[86:89], v[174:177], v[230:233], v[86:89]
	v_mfma_f32_16x16x32_bf16 v[82:85], v[202:205], v[226:229], 0
	v_mfma_f32_16x16x32_bf16 v[82:85], v[206:209], v[230:233], v[82:85]
	v_mfma_f32_16x16x32_bf16 v[70:73], v[170:173], v[234:237], 0
	v_mfma_f32_16x16x32_bf16 v[70:73], v[174:177], v[238:241], v[70:73]
	v_mfma_f32_16x16x32_bf16 v[66:69], v[202:205], v[234:237], 0
	v_mfma_f32_16x16x32_bf16 v[66:69], v[206:209], v[238:241], v[66:69]
	s_setprio 0
	s_barrier
	s_add_i32 s75, s75, s23
	v_lshl_add_u64 v[178:179], vcc, 0, v[0:1]
	s_mov_b32 m0, s75
	ds_read_b128 v[210:213], v201 offset:16384
	ds_read_b128 v[214:217], v201 offset:17408
	ds_read_b128 v[218:221], v201 offset:18432
	ds_read_b128 v[222:225], v201 offset:19456
	ds_read_b128 v[226:229], v201 offset:20480
	ds_read_b128 v[230:233], v201 offset:21504
	ds_read_b128 v[234:237], v201 offset:22528
	ds_read_b128 v[238:241], v201 offset:23552
	global_load_lds_dwordx4 v[178:179], off
	s_add_i32 m0, s75, 0x2000
	v_lshl_add_u64 v[242:243], vcc, 0, v[162:163]
	s_add_u32 vcc_lo, vcc_lo, s84
	s_addc_u32 vcc_hi, vcc_hi, 0
	s_add_i32 s43, s43, s23
	global_load_lds_dwordx4 v[242:243], off
	v_lshl_add_u64 v[244:245], vcc, 0, v[0:1]
	s_mov_b32 m0, s43
	v_lshl_add_u64 v[246:247], vcc, 0, v[162:163]
	global_load_lds_dwordx4 v[244:245], off
	s_add_i32 m0, s43, 0x2000
	v_lshl_add_u64 v[248:249], s[14:15], 0, v[158:159]
	global_load_lds_dwordx4 v[246:247], off
	s_mov_b32 m0, s56
	v_lshl_add_u64 v[250:251], s[14:15], 0, v[160:161]
	global_load_lds_dwordx4 v[248:249], off
	s_mov_b32 m0, s82
	s_nop 0
	global_load_lds_dwordx4 v[250:251], off
	s_waitcnt vmcnt(8)
	s_waitcnt lgkmcnt(0)
	s_barrier
; #define PG8_STAGE(bufoff, gbase, voff) do { _Pragma("unroll") for (int _i = 0; _i < 2; ++_i) \
;         __builtin_amdgcn_global_load_lds((const unsigned*)((const char*)(gbase) + (voff)[_i]), (PG8_LAS unsigned*)(lds + (bufoff) + ldsw + _i * 8192), 16, 0, 0); } while (0)
; #define PG8_LDA(dst, b, h) do { _Pragma("unroll") for (int m = 0; m < 4; ++m) _Pragma("unroll") for (int k = 0; k < 2; ++k) dst[m][k] = *(const PG8_LAS bf16x8*)(lds + PG8_SA(b, h) + aoff + m * 2048 + k * 1024); } while (0)
; #define PG8_LDB(dst, b, h) do { _Pragma("unroll") for (int n = 0; n < 2; ++n) _Pragma("unroll") for (int k = 0; k < 2; ++k) dst[n][k] = *(const PG8_LAS bf16x8*)(lds + PG8_SB(b, h) + boff + n * 2048 + k * 1024); } while (0)
; #define PG8_MMA(ai, bj, At, Bt) do { __builtin_amdgcn_s_setprio(1); _Pragma("unroll") for (int m = 0; m < 4; ++m) _Pragma("unroll") for (int n = 0; n < 2; ++n) _Pragma("unroll") for (int k = 0; k < 2; ++k) \
;         acc[ai][bj][m][n] = __builtin_amdgcn_mfma_f32_16x16x32_bf16(Bt[n][k], At[m][k], acc[ai][bj][m][n], 0, 0, 0); __builtin_amdgcn_s_setprio(0); } while (0)
; #define PG8_WAIT_V(n) asm volatile("s_waitcnt vmcnt(" #n ")" ::: "memory")
; #define PG8_WAIT_L(n) asm volatile("s_waitcnt lgkmcnt(" #n ")" ::: "memory")
; #define PG8_BAR __builtin_amdgcn_s_barrier()
; #define PG8_SCHED __builtin_amdgcn_sched_barrier(0)
; template <class Epi, class Sched, bool ALIGN_EPI = false, bool SP2 = false>
; __device__ __forceinline__ void gemm_phase(PG8_LAS unsigned char* lds, const Gemm g, const Sched& S, const Epi& E) {
;     ...
;             PG8_WAIT_V(8); PG8_WAIT_L(0); PG8_BAR; PG8_MMA(1, 0, At, B0); PG8_MMA(1, 1, At, B1); PG8_BAR; PG8_SCHED;
;             PG8_LDB(B0, 1, 0); PG8_LDB(B1, 1, 1); PG8_SCHED; PG8_LDA(At, 1, 0); PG8_STAGE(PG8_SA(0, 1), a2 + hstep, voffA);
;             PG8_WAIT_V(8); PG8_WAIT_L(0); PG8_BAR; PG8_MMA(0, 0, At, B0); PG8_MMA(0, 1, At, B1); PG8_BAR; PG8_SCHED;
	s_setprio 1
	v_mfma_f32_16x16x32_bf16 v[62:65], v[130:133], v[210:213], 0
	v_mfma_f32_16x16x32_bf16 v[62:65], v[134:137], v[214:217], v[62:65]
	v_mfma_f32_16x16x32_bf16 v[58:61], v[138:141], v[210:213], 0
	v_mfma_f32_16x16x32_bf16 v[58:61], v[142:145], v[214:217], v[58:61]
	v_mfma_f32_16x16x32_bf16 v[46:49], v[130:133], v[218:221], 0
	v_mfma_f32_16x16x32_bf16 v[46:49], v[134:137], v[222:225], v[46:49]
	v_mfma_f32_16x16x32_bf16 v[42:45], v[138:141], v[218:221], 0
	v_mfma_f32_16x16x32_bf16 v[42:45], v[142:145], v[222:225], v[42:45]
	v_mfma_f32_16x16x32_bf16 v[30:33], v[130:133], v[226:229], 0
	v_mfma_f32_16x16x32_bf16 v[30:33], v[134:137], v[230:233], v[30:33]
	v_mfma_f32_16x16x32_bf16 v[26:29], v[138:141], v[226:229], 0
	v_mfma_f32_16x16x32_bf16 v[26:29], v[142:145], v[230:233], v[26:29]
	v_mfma_f32_16x16x32_bf16 v[14:17], v[130:133], v[234:237], 0
	v_mfma_f32_16x16x32_bf16 v[14:17], v[134:137], v[238:241], v[14:17]
	v_mfma_f32_16x16x32_bf16 v[10:13], v[138:141], v[234:237], 0
	v_mfma_f32_16x16x32_bf16 v[10:13], v[142:145], v[238:241], v[10:13]
	v_mfma_f32_16x16x32_bf16 v[54:57], v[170:173], v[210:213], 0
	v_mfma_f32_16x16x32_bf16 v[54:57], v[174:177], v[214:217], v[54:57]
	v_mfma_f32_16x16x32_bf16 v[50:53], v[202:205], v[210:213], 0
	v_mfma_f32_16x16x32_bf16 v[50:53], v[206:209], v[214:217], v[50:53]
	v_mfma_f32_16x16x32_bf16 v[38:41], v[170:173], v[218:221], 0
	v_mfma_f32_16x16x32_bf16 v[38:41], v[174:177], v[222:225], v[38:41]
	v_mfma_f32_16x16x32_bf16 v[34:37], v[202:205], v[218:221], 0
	v_mfma_f32_16x16x32_bf16 v[34:37], v[206:209], v[222:225], v[34:37]
	v_mfma_f32_16x16x32_bf16 v[22:25], v[170:173], v[226:229], 0
	v_mfma_f32_16x16x32_bf16 v[22:25], v[174:177], v[230:233], v[22:25]
	v_mfma_f32_16x16x32_bf16 v[18:21], v[202:205], v[226:229], 0
	v_mfma_f32_16x16x32_bf16 v[18:21], v[206:209], v[230:233], v[18:21]
	v_mfma_f32_16x16x32_bf16 v[6:9], v[170:173], v[234:237], 0
	v_mfma_f32_16x16x32_bf16 v[6:9], v[174:177], v[238:241], v[6:9]
	v_mfma_f32_16x16x32_bf16 v[2:5], v[202:205], v[234:237], 0
	v_mfma_f32_16x16x32_bf16 v[2:5], v[206:209], v[238:241], v[2:5]
	s_setprio 0
	s_barrier
	s_add_i32 s43, 0, 0x18000
	s_add_i32 s75, 0, 0x1c000
	v_add_u32_e32 v142, s43, v199
	v_add_u32_e32 v206, s75, v199
	ds_read_b128 v[130:133], v142
	ds_read_b128 v[134:137], v142 offset:1024
	ds_read_b128 v[138:141], v142 offset:2048
	ds_read_b128 v[142:145], v142 offset:3072
	ds_read_b128 v[170:173], v206
	ds_read_b128 v[174:177], v206 offset:1024
	ds_read_b128 v[202:205], v206 offset:2048
	ds_read_b128 v[206:209], v206 offset:3072
	s_add_u32 s14, s14, s84
	s_addc_u32 s15, s15, 0
	s_mov_b32 m0, s83
	v_lshl_add_u64 v[252:253], s[14:15], 0, v[158:159]
	ds_read_b128 v[210:213], v201 offset:32768
	ds_read_b128 v[214:217], v201 offset:33792
	ds_read_b128 v[218:221], v201 offset:34816
	ds_read_b128 v[222:225], v201 offset:35840
	ds_read_b128 v[226:229], v201 offset:36864
	ds_read_b128 v[230:233], v201 offset:37888
	ds_read_b128 v[234:237], v201 offset:38912
	ds_read_b128 v[238:241], v201 offset:39936
	global_load_lds_dwordx4 v[252:253], off
	v_lshl_add_u64 v[252:253], s[14:15], 0, v[160:161]
	s_mov_b32 m0, s24
	s_nop 0
	global_load_lds_dwordx4 v[252:253], off
	s_waitcnt vmcnt(8)
	s_waitcnt lgkmcnt(0)
	s_barrier
	s_setprio 1
	v_mfma_f32_16x16x32_bf16 v[126:129], v[130:133], v[210:213], v[126:129]
	v_mfma_f32_16x16x32_bf16 v[126:129], v[134:137], v[214:217], v[126:129]
	v_mfma_f32_16x16x32_bf16 v[122:125], v[138:141], v[210:213], v[122:125]
	v_mfma_f32_16x16x32_bf16 v[122:125], v[142:145], v[214:217], v[122:125]
	v_mfma_f32_16x16x32_bf16 v[110:113], v[130:133], v[218:221], v[110:113]
	v_mfma_f32_16x16x32_bf16 v[110:113], v[134:137], v[222:225], v[110:113]
	v_mfma_f32_16x16x32_bf16 v[106:109], v[138:141], v[218:221], v[106:109]
	v_mfma_f32_16x16x32_bf16 v[106:109], v[142:145], v[222:225], v[106:109]
	v_mfma_f32_16x16x32_bf16 v[94:97], v[130:133], v[226:229], v[94:97]
	v_mfma_f32_16x16x32_bf16 v[94:97], v[134:137], v[230:233], v[94:97]
	v_mfma_f32_16x16x32_bf16 v[90:93], v[138:141], v[226:229], v[90:93]
	v_mfma_f32_16x16x32_bf16 v[90:93], v[142:145], v[230:233], v[90:93]
	v_mfma_f32_16x16x32_bf16 v[78:81], v[130:133], v[234:237], v[78:81]
	v_mfma_f32_16x16x32_bf16 v[78:81], v[134:137], v[238:241], v[78:81]
	v_mfma_f32_16x16x32_bf16 v[74:77], v[138:141], v[234:237], v[74:77]
	v_mfma_f32_16x16x32_bf16 v[74:77], v[142:145], v[238:241], v[74:77]
	v_mfma_f32_16x16x32_bf16 v[118:121], v[170:173], v[210:213], v[118:121]
	v_mfma_f32_16x16x32_bf16 v[118:121], v[174:177], v[214:217], v[118:121]
	v_mfma_f32_16x16x32_bf16 v[114:117], v[202:205], v[210:213], v[114:117]
	v_mfma_f32_16x16x32_bf16 v[114:117], v[206:209], v[214:217], v[114:117]
	v_mfma_f32_16x16x32_bf16 v[102:105], v[170:173], v[218:221], v[102:105]
	v_mfma_f32_16x16x32_bf16 v[102:105], v[174:177], v[222:225], v[102:105]
	v_mfma_f32_16x16x32_bf16 v[98:101], v[202:205], v[218:221], v[98:101]
	v_mfma_f32_16x16x32_bf16 v[98:101], v[206:209], v[222:225], v[98:101]
	v_mfma_f32_16x16x32_bf16 v[86:89], v[170:173], v[226:229], v[86:89]
	v_mfma_f32_16x16x32_bf16 v[86:89], v[174:177], v[230:233], v[86:89]
	v_mfma_f32_16x16x32_bf16 v[82:85], v[202:205], v[226:229], v[82:85]
	v_mfma_f32_16x16x32_bf16 v[82:85], v[206:209], v[230:233], v[82:85]
	v_mfma_f32_16x16x32_bf16 v[70:73], v[170:173], v[234:237], v[70:73]
	v_mfma_f32_16x16x32_bf16 v[70:73], v[174:177], v[238:241], v[70:73]
	v_mfma_f32_16x16x32_bf16 v[66:69], v[202:205], v[234:237], v[66:69]
	v_mfma_f32_16x16x32_bf16 v[66:69], v[206:209], v[238:241], v[66:69]
	s_setprio 0
	s_barrier
; #define PG8_STAGE(bufoff, gbase, voff) do { _Pragma("unroll") for (int _i = 0; _i < 2; ++_i) \
;         __builtin_amdgcn_global_load_lds((const unsigned*)((const char*)(gbase) + (voff)[_i]), (PG8_LAS unsigned*)(lds + (bufoff) + ldsw + _i * 8192), 16, 0, 0); } while (0)
; #define PG8_LDA(dst, b, h) do { _Pragma("unroll") for (int m = 0; m < 4; ++m) _Pragma("unroll") for (int k = 0; k < 2; ++k) dst[m][k] = *(const PG8_LAS bf16x8*)(lds + PG8_SA(b, h) + aoff + m * 2048 + k * 1024); } while (0)
; #define PG8_LDB(dst, b, h) do { _Pragma("unroll") for (int n = 0; n < 2; ++n) _Pragma("unroll") for (int k = 0; k < 2; ++k) dst[n][k] = *(const PG8_LAS bf16x8*)(lds + PG8_SB(b, h) + boff + n * 2048 + k * 1024); } while (0)
; template <class Epi, class Sched, bool ALIGN_EPI = false, bool SP2 = false>
; __device__ __forceinline__ void gemm_phase(PG8_LAS unsigned char* lds, const Gemm g, const Sched& S, const Epi& E) {
;     ...
;         for (int t = 0; t < nt; t += 2) {
;             const bool last = (t == nt - 2);
;             const char* a1 = cA + (size_t)(t + 1) * kstep;
;             const char* a2 = last ? nA : cA + (size_t)(t + 2) * kstep; const char* b2 = last ? nB : cB + (size_t)(t + 2) * kstep;
;             const char* a3 = a2 + kstep; const char* b3 = b2 + kstep;
;             if (last && has_next) S.a_ready(nxt);
;             if constexpr (SP2) {
;             PG8_LDB(B0, 0, 0); PG8_LDB(B1, 0, 1); PG8_SCHED; PG8_LDA(At, 0, 0); PG8_STAGE(PG8_SA(1, 1), a1 + hstep, voffA);
;             PG8_WAIT_V(8); PG8_WAIT_L(0); PG8_BAR; PG8_MMA(0, 0, At, B0); PG8_MMA(0, 1, At, B1); PG8_BAR; PG8_SCHED;
;             PG8_LDA(At, 0, 1); PG8_STAGE(PG8_SB(0, 0), b2, voffB); PG8_STAGE(PG8_SB(0, 1), b2 + hstep, voffB); PG8_STAGE(PG8_SA(0, 0), a2, voffA);
;             PG8_WAIT_V(8); PG8_WAIT_L(0); PG8_BAR; PG8_MMA(1, 0, At, B0); PG8_MMA(1, 1, At, B1); PG8_BAR; PG8_SCHED;
;             PG8_LDB(B0, 1, 0); PG8_LDB(B1, 1, 1); PG8_SCHED; PG8_LDA(At, 1, 0); PG8_STAGE(PG8_SA(0, 1), a2 + hstep, voffA);
;             PG8_WAIT_V(8); PG8_WAIT_L(0); PG8_BAR; PG8_MMA(0, 0, At, B0); PG8_MMA(0, 1, At, B1); PG8_BAR; PG8_SCHED;
;             PG8_LDA(At, 1, 1); PG8_STAGE(PG8_SB(1, 0), b3, voffB); PG8_STAGE(PG8_SB(1, 1), b3 + hstep, voffB); PG8_STAGE(PG8_SA(1, 0), a3, voffA);
;             PG8_WAIT_V(8); PG8_WAIT_L(0); PG8_BAR; PG8_MMA(1, 0, At, B0); PG8_MMA(1, 1, At, B1); PG8_BAR; PG8_SCHED;
	s_add_i32 s14, s43, s23
	v_lshl_add_u64 v[178:179], v[178:179], 0, s[94:95]
	s_mov_b32 m0, s14
	ds_read_b128 v[210:213], v201 offset:49152
	ds_read_b128 v[214:217], v201 offset:50176
	ds_read_b128 v[218:221], v201 offset:51200
	ds_read_b128 v[222:225], v201 offset:52224
	ds_read_b128 v[226:229], v201 offset:53248
	ds_read_b128 v[230:233], v201 offset:54272
	ds_read_b128 v[234:237], v201 offset:55296
	ds_read_b128 v[238:241], v201 offset:56320
	global_load_lds_dwordx4 v[178:179], off
	v_lshl_add_u64 v[178:179], v[242:243], 0, s[94:95]
	s_add_i32 m0, s14, 0x2000
	s_add_i32 s14, s75, s23
	global_load_lds_dwordx4 v[178:179], off
	v_lshl_add_u64 v[178:179], v[244:245], 0, s[94:95]
	s_mov_b32 m0, s14
	s_nop 0
	global_load_lds_dwordx4 v[178:179], off
	v_lshl_add_u64 v[178:179], v[246:247], 0, s[94:95]
	s_add_i32 m0, s14, 0x2000
	s_nop 0
	global_load_lds_dwordx4 v[178:179], off
	v_lshl_add_u64 v[178:179], v[248:249], 0, s[94:95]
	s_mov_b32 m0, s63
	s_nop 0
	global_load_lds_dwordx4 v[178:179], off
	v_lshl_add_u64 v[178:179], v[250:251], 0, s[94:95]
	s_mov_b32 m0, s70
	s_nop 0
	global_load_lds_dwordx4 v[178:179], off
	s_waitcnt vmcnt(8)
	s_waitcnt lgkmcnt(0)
	s_barrier
	s_setprio 1
	v_mfma_f32_16x16x32_bf16 v[62:65], v[130:133], v[210:213], v[62:65]
	v_mfma_f32_16x16x32_bf16 v[62:65], v[134:137], v[214:217], v[62:65]
	v_mfma_f32_16x16x32_bf16 v[58:61], v[138:141], v[210:213], v[58:61]
	v_mfma_f32_16x16x32_bf16 v[58:61], v[142:145], v[214:217], v[58:61]
	v_mfma_f32_16x16x32_bf16 v[46:49], v[130:133], v[218:221], v[46:49]
	v_mfma_f32_16x16x32_bf16 v[46:49], v[134:137], v[222:225], v[46:49]
	v_mfma_f32_16x16x32_bf16 v[42:45], v[138:141], v[218:221], v[42:45]
	v_mfma_f32_16x16x32_bf16 v[42:45], v[142:145], v[222:225], v[42:45]
	v_mfma_f32_16x16x32_bf16 v[30:33], v[130:133], v[226:229], v[30:33]
	v_mfma_f32_16x16x32_bf16 v[30:33], v[134:137], v[230:233], v[30:33]
	v_mfma_f32_16x16x32_bf16 v[26:29], v[138:141], v[226:229], v[26:29]
	v_mfma_f32_16x16x32_bf16 v[26:29], v[142:145], v[230:233], v[26:29]
	v_mfma_f32_16x16x32_bf16 v[14:17], v[130:133], v[234:237], v[14:17]
	v_mfma_f32_16x16x32_bf16 v[14:17], v[134:137], v[238:241], v[14:17]
	v_mfma_f32_16x16x32_bf16 v[10:13], v[138:141], v[234:237], v[10:13]
	v_mfma_f32_16x16x32_bf16 v[10:13], v[142:145], v[238:241], v[10:13]
	v_mfma_f32_16x16x32_bf16 v[54:57], v[170:173], v[210:213], v[54:57]
	v_mfma_f32_16x16x32_bf16 v[54:57], v[174:177], v[214:217], v[54:57]
	v_mfma_f32_16x16x32_bf16 v[50:53], v[202:205], v[210:213], v[50:53]
	v_mfma_f32_16x16x32_bf16 v[50:53], v[206:209], v[214:217], v[50:53]
	v_mfma_f32_16x16x32_bf16 v[38:41], v[170:173], v[218:221], v[38:41]
	v_mfma_f32_16x16x32_bf16 v[38:41], v[174:177], v[222:225], v[38:41]
	v_mfma_f32_16x16x32_bf16 v[34:37], v[202:205], v[218:221], v[34:37]
	v_mfma_f32_16x16x32_bf16 v[34:37], v[206:209], v[222:225], v[34:37]
	v_mfma_f32_16x16x32_bf16 v[22:25], v[170:173], v[226:229], v[22:25]
	v_mfma_f32_16x16x32_bf16 v[22:25], v[174:177], v[230:233], v[22:25]
	v_mfma_f32_16x16x32_bf16 v[18:21], v[202:205], v[226:229], v[18:21]
	v_mfma_f32_16x16x32_bf16 v[18:21], v[206:209], v[230:233], v[18:21]
	v_mfma_f32_16x16x32_bf16 v[6:9], v[170:173], v[234:237], v[6:9]
	v_mfma_f32_16x16x32_bf16 v[6:9], v[174:177], v[238:241], v[6:9]
	v_mfma_f32_16x16x32_bf16 v[2:5], v[202:205], v[234:237], v[2:5]
	v_mfma_f32_16x16x32_bf16 v[2:5], v[206:209], v[238:241], v[2:5]
	s_setprio 0
	s_barrier
	s_add_u32 s12, s12, 0x100
	s_addc_u32 s13, s13, 0
	s_add_u32 s16, s16, 0x100
	s_addc_u32 s17, s17, 0
	s_cmp_ge_u32 s42, s28
	s_mov_b32 s14, s42
	s_cbranch_scc0 .LBB0_322
	s_branch .Lk_done
.LBB0_322:
	s_add_i32 s42, s14, 2
	s_add_u32 s43, s12, 0x80
	s_addc_u32 s15, s13, 0
	s_add_i32 s75, 0, 0x10000
	s_cmp_eq_u32 s25, s14
	s_cselect_b32 s15, s55, s15
	s_cselect_b32 s14, s54, s43
	s_cselect_b32 vcc_hi, s65, s17
	s_cselect_b32 vcc_lo, s64, s16
	s_add_i32 s43, 0, 0x14000
	v_add_u32_e32 v142, s75, v199
	v_add_u32_e32 v178, s43, v199
	ds_read_b128 v[130:133], v142
	ds_read_b128 v[134:137], v142 offset:1024
	ds_read_b128 v[138:141], v142 offset:2048
	ds_read_b128 v[142:145], v142 offset:3072
	ds_read_b128 v[170:173], v178
	ds_read_b128 v[174:177], v178 offset:1024
	ds_read_b128 v[202:205], v178 offset:2048
	ds_read_b128 v[206:209], v178 offset:3072
	v_lshl_add_u64 v[178:179], s[12:13], 0, v[166:167]
	s_add_i32 m0, s56, 0xc000
	ds_read_b128 v[210:213], v201
	ds_read_b128 v[214:217], v201 offset:1024
	ds_read_b128 v[218:221], v201 offset:2048
	ds_read_b128 v[222:225], v201 offset:3072
	ds_read_b128 v[226:229], v201 offset:4096
	ds_read_b128 v[230:233], v201 offset:5120
	ds_read_b128 v[234:237], v201 offset:6144
	ds_read_b128 v[238:241], v201 offset:7168
	global_load_lds_dwordx4 v[178:179], off
	v_lshl_add_u64 v[178:179], s[12:13], 0, v[168:169]
	s_add_i32 m0, s56, 0xe000
	s_nop 0
	global_load_lds_dwordx4 v[178:179], off
	s_waitcnt vmcnt(8)
	s_waitcnt lgkmcnt(0)
	s_barrier
; #define PG8_STAGE(bufoff, gbase, voff) do { _Pragma("unroll") for (int _i = 0; _i < 2; ++_i) \
;         __builtin_amdgcn_global_load_lds((const unsigned*)((const char*)(gbase) + (voff)[_i]), (PG8_LAS unsigned*)(lds + (bufoff) + ldsw + _i * 8192), 16, 0, 0); } while (0)
; #define PG8_LDA(dst, b, h) do { _Pragma("unroll") for (int m = 0; m < 4; ++m) _Pragma("unroll") for (int k = 0; k < 2; ++k) dst[m][k] = *(const PG8_LAS bf16x8*)(lds + PG8_SA(b, h) + aoff + m * 2048 + k * 1024); } while (0)
; #define PG8_MMA(ai, bj, At, Bt) do { __builtin_amdgcn_s_setprio(1); _Pragma("unroll") for (int m = 0; m < 4; ++m) _Pragma("unroll") for (int n = 0; n < 2; ++n) _Pragma("unroll") for (int k = 0; k < 2; ++k) \
;         acc[ai][bj][m][n] = __builtin_amdgcn_mfma_f32_16x16x32_bf16(Bt[n][k], At[m][k], acc[ai][bj][m][n], 0, 0, 0); __builtin_amdgcn_s_setprio(0); } while (0)
; #define PG8_WAIT_V(n) asm volatile("s_waitcnt vmcnt(" #n ")" ::: "memory")
; #define PG8_WAIT_L(n) asm volatile("s_waitcnt lgkmcnt(" #n ")" ::: "memory")
; #define PG8_BAR __builtin_amdgcn_s_barrier()
; #define PG8_SCHED __builtin_amdgcn_sched_barrier(0)
; template <class Epi, class Sched, bool ALIGN_EPI = false, bool SP2 = false>
; __device__ __forceinline__ void gemm_phase(PG8_LAS unsigned char* lds, const Gemm g, const Sched& S, const Epi& E) {
;     ...
;             PG8_WAIT_V(8); PG8_WAIT_L(0); PG8_BAR; PG8_MMA(0, 0, At, B0); PG8_MMA(0, 1, At, B1); PG8_BAR; PG8_SCHED;
;             PG8_LDA(At, 0, 1); PG8_STAGE(PG8_SB(0, 0), b2, voffB); PG8_STAGE(PG8_SB(0, 1), b2 + hstep, voffB); PG8_STAGE(PG8_SA(0, 0), a2, voffA);
;             PG8_WAIT_V(8); PG8_WAIT_L(0); PG8_BAR; PG8_MMA(1, 0, At, B0); PG8_MMA(1, 1, At, B1); PG8_BAR; PG8_SCHED;
	s_setprio 1
	v_mfma_f32_16x16x32_bf16 v[126:129], v[130:133], v[210:213], v[126:129]
	v_mfma_f32_16x16x32_bf16 v[126:129], v[134:137], v[214:217], v[126:129]
	v_mfma_f32_16x16x32_bf16 v[122:125], v[138:141], v[210:213], v[122:125]
	v_mfma_f32_16x16x32_bf16 v[122:125], v[142:145], v[214:217], v[122:125]
	v_mfma_f32_16x16x32_bf16 v[110:113], v[130:133], v[218:221], v[110:113]
	v_mfma_f32_16x16x32_bf16 v[110:113], v[134:137], v[222:225], v[110:113]
	v_mfma_f32_16x16x32_bf16 v[106:109], v[138:141], v[218:221], v[106:109]
	v_mfma_f32_16x16x32_bf16 v[106:109], v[142:145], v[222:225], v[106:109]
	v_mfma_f32_16x16x32_bf16 v[94:97], v[130:133], v[226:229], v[94:97]
	v_mfma_f32_16x16x32_bf16 v[94:97], v[134:137], v[230:233], v[94:97]
	v_mfma_f32_16x16x32_bf16 v[90:93], v[138:141], v[226:229], v[90:93]
	v_mfma_f32_16x16x32_bf16 v[90:93], v[142:145], v[230:233], v[90:93]
	v_mfma_f32_16x16x32_bf16 v[78:81], v[130:133], v[234:237], v[78:81]
	v_mfma_f32_16x16x32_bf16 v[78:81], v[134:137], v[238:241], v[78:81]
	v_mfma_f32_16x16x32_bf16 v[74:77], v[138:141], v[234:237], v[74:77]
	v_mfma_f32_16x16x32_bf16 v[74:77], v[142:145], v[238:241], v[74:77]
	v_mfma_f32_16x16x32_bf16 v[118:121], v[170:173], v[210:213], v[118:121]
	v_mfma_f32_16x16x32_bf16 v[118:121], v[174:177], v[214:217], v[118:121]
	v_mfma_f32_16x16x32_bf16 v[114:117], v[202:205], v[210:213], v[114:117]
	v_mfma_f32_16x16x32_bf16 v[114:117], v[206:209], v[214:217], v[114:117]
	v_mfma_f32_16x16x32_bf16 v[102:105], v[170:173], v[218:221], v[102:105]
	v_mfma_f32_16x16x32_bf16 v[102:105], v[174:177], v[222:225], v[102:105]
	v_mfma_f32_16x16x32_bf16 v[98:101], v[202:205], v[218:221], v[98:101]
	v_mfma_f32_16x16x32_bf16 v[98:101], v[206:209], v[222:225], v[98:101]
	v_mfma_f32_16x16x32_bf16 v[86:89], v[170:173], v[226:229], v[86:89]
	v_mfma_f32_16x16x32_bf16 v[86:89], v[174:177], v[230:233], v[86:89]
	v_mfma_f32_16x16x32_bf16 v[82:85], v[202:205], v[226:229], v[82:85]
	v_mfma_f32_16x16x32_bf16 v[82:85], v[206:209], v[230:233], v[82:85]
	v_mfma_f32_16x16x32_bf16 v[70:73], v[170:173], v[234:237], v[70:73]
	v_mfma_f32_16x16x32_bf16 v[70:73], v[174:177], v[238:241], v[70:73]
	v_mfma_f32_16x16x32_bf16 v[66:69], v[202:205], v[234:237], v[66:69]
	v_mfma_f32_16x16x32_bf16 v[66:69], v[206:209], v[238:241], v[66:69]
	s_setprio 0
	s_barrier
	s_add_i32 s75, s75, s23
	v_lshl_add_u64 v[178:179], vcc, 0, v[0:1]
	s_mov_b32 m0, s75
	ds_read_b128 v[210:213], v201 offset:16384
	ds_read_b128 v[214:217], v201 offset:17408
	ds_read_b128 v[218:221], v201 offset:18432
	ds_read_b128 v[222:225], v201 offset:19456
	ds_read_b128 v[226:229], v201 offset:20480
	ds_read_b128 v[230:233], v201 offset:21504
	ds_read_b128 v[234:237], v201 offset:22528
	ds_read_b128 v[238:241], v201 offset:23552
	global_load_lds_dwordx4 v[178:179], off
	s_add_i32 m0, s75, 0x2000
	v_lshl_add_u64 v[242:243], vcc, 0, v[162:163]
	s_add_u32 vcc_lo, vcc_lo, s84
	s_addc_u32 vcc_hi, vcc_hi, 0
	s_add_i32 s43, s43, s23
	global_load_lds_dwordx4 v[242:243], off
	v_lshl_add_u64 v[244:245], vcc, 0, v[0:1]
	s_mov_b32 m0, s43
	v_lshl_add_u64 v[246:247], vcc, 0, v[162:163]
	global_load_lds_dwordx4 v[244:245], off
	s_add_i32 m0, s43, 0x2000
	v_lshl_add_u64 v[248:249], s[14:15], 0, v[158:159]
	global_load_lds_dwordx4 v[246:247], off
	s_mov_b32 m0, s56
	v_lshl_add_u64 v[250:251], s[14:15], 0, v[160:161]
	global_load_lds_dwordx4 v[248:249], off
	s_mov_b32 m0, s82
	s_nop 0
	global_load_lds_dwordx4 v[250:251], off
	s_waitcnt vmcnt(8)
	s_waitcnt lgkmcnt(0)
	s_barrier
	s_setprio 1
	v_mfma_f32_16x16x32_bf16 v[62:65], v[130:133], v[210:213], v[62:65]
	v_mfma_f32_16x16x32_bf16 v[62:65], v[134:137], v[214:217], v[62:65]
	v_mfma_f32_16x16x32_bf16 v[58:61], v[138:141], v[210:213], v[58:61]
	v_mfma_f32_16x16x32_bf16 v[58:61], v[142:145], v[214:217], v[58:61]
	v_mfma_f32_16x16x32_bf16 v[46:49], v[130:133], v[218:221], v[46:49]
	v_mfma_f32_16x16x32_bf16 v[46:49], v[134:137], v[222:225], v[46:49]
	v_mfma_f32_16x16x32_bf16 v[42:45], v[138:141], v[218:221], v[42:45]
	v_mfma_f32_16x16x32_bf16 v[42:45], v[142:145], v[222:225], v[42:45]
	v_mfma_f32_16x16x32_bf16 v[30:33], v[130:133], v[226:229], v[30:33]
	v_mfma_f32_16x16x32_bf16 v[30:33], v[134:137], v[230:233], v[30:33]
	v_mfma_f32_16x16x32_bf16 v[26:29], v[138:141], v[226:229], v[26:29]
	v_mfma_f32_16x16x32_bf16 v[26:29], v[142:145], v[230:233], v[26:29]
	v_mfma_f32_16x16x32_bf16 v[14:17], v[130:133], v[234:237], v[14:17]
	v_mfma_f32_16x16x32_bf16 v[14:17], v[134:137], v[238:241], v[14:17]
	v_mfma_f32_16x16x32_bf16 v[10:13], v[138:141], v[234:237], v[10:13]
	v_mfma_f32_16x16x32_bf16 v[10:13], v[142:145], v[238:241], v[10:13]
	v_mfma_f32_16x16x32_bf16 v[54:57], v[170:173], v[210:213], v[54:57]
	v_mfma_f32_16x16x32_bf16 v[54:57], v[174:177], v[214:217], v[54:57]
	v_mfma_f32_16x16x32_bf16 v[50:53], v[202:205], v[210:213], v[50:53]
	v_mfma_f32_16x16x32_bf16 v[50:53], v[206:209], v[214:217], v[50:53]
	v_mfma_f32_16x16x32_bf16 v[38:41], v[170:173], v[218:221], v[38:41]
	v_mfma_f32_16x16x32_bf16 v[38:41], v[174:177], v[222:225], v[38:41]
	v_mfma_f32_16x16x32_bf16 v[34:37], v[202:205], v[218:221], v[34:37]
	v_mfma_f32_16x16x32_bf16 v[34:37], v[206:209], v[222:225], v[34:37]
	v_mfma_f32_16x16x32_bf16 v[22:25], v[170:173], v[226:229], v[22:25]
	v_mfma_f32_16x16x32_bf16 v[22:25], v[174:177], v[230:233], v[22:25]
	v_mfma_f32_16x16x32_bf16 v[18:21], v[202:205], v[226:229], v[18:21]
	v_mfma_f32_16x16x32_bf16 v[18:21], v[206:209], v[230:233], v[18:21]
	v_mfma_f32_16x16x32_bf16 v[6:9], v[170:173], v[234:237], v[6:9]
	v_mfma_f32_16x16x32_bf16 v[6:9], v[174:177], v[238:241], v[6:9]
	v_mfma_f32_16x16x32_bf16 v[2:5], v[202:205], v[234:237], v[2:5]
	v_mfma_f32_16x16x32_bf16 v[2:5], v[206:209], v[238:241], v[2:5]
	s_setprio 0
	s_barrier
; #define PG8_STAGE(bufoff, gbase, voff) do { _Pragma("unroll") for (int _i = 0; _i < 2; ++_i) \
;         __builtin_amdgcn_global_load_lds((const unsigned*)((const char*)(gbase) + (voff)[_i]), (PG8_LAS unsigned*)(lds + (bufoff) + ldsw + _i * 8192), 16, 0, 0); } while (0)
; #define PG8_LDA(dst, b, h) do { _Pragma("unroll") for (int m = 0; m < 4; ++m) _Pragma("unroll") for (int k = 0; k < 2; ++k) dst[m][k] = *(const PG8_LAS bf16x8*)(lds + PG8_SA(b, h) + aoff + m * 2048 + k * 1024); } while (0)
; #define PG8_LDB(dst, b, h) do { _Pragma("unroll") for (int n = 0; n < 2; ++n) _Pragma("unroll") for (int k = 0; k < 2; ++k) dst[n][k] = *(const PG8_LAS bf16x8*)(lds + PG8_SB(b, h) + boff + n * 2048 + k * 1024); } while (0)
; #define PG8_MMA(ai, bj, At, Bt) do { __builtin_amdgcn_s_setprio(1); _Pragma("unroll") for (int m = 0; m < 4; ++m) _Pragma("unroll") for (int n = 0; n < 2; ++n) _Pragma("unroll") for (int k = 0; k < 2; ++k) \
;         acc[ai][bj][m][n] = __builtin_amdgcn_mfma_f32_16x16x32_bf16(Bt[n][k], At[m][k], acc[ai][bj][m][n], 0, 0, 0); __builtin_amdgcn_s_setprio(0); } while (0)
; #define PG8_WAIT_V(n) asm volatile("s_waitcnt vmcnt(" #n ")" ::: "memory")
; #define PG8_WAIT_L(n) asm volatile("s_waitcnt lgkmcnt(" #n ")" ::: "memory")
; #define PG8_BAR __builtin_amdgcn_s_barrier()
; #define PG8_SCHED __builtin_amdgcn_sched_barrier(0)
; template <class Epi, class Sched, bool ALIGN_EPI = false, bool SP2 = false>
; __device__ __forceinline__ void gemm_phase(PG8_LAS unsigned char* lds, const Gemm g, const Sched& S, const Epi& E) {
;     ...
;             PG8_LDB(B0, 1, 0); PG8_LDB(B1, 1, 1); PG8_SCHED; PG8_LDA(At, 1, 0); PG8_STAGE(PG8_SA(0, 1), a2 + hstep, voffA);
;             PG8_WAIT_V(8); PG8_WAIT_L(0); PG8_BAR; PG8_MMA(0, 0, At, B0); PG8_MMA(0, 1, At, B1); PG8_BAR; PG8_SCHED;
;             PG8_LDA(At, 1, 1); PG8_STAGE(PG8_SB(1, 0), b3, voffB); PG8_STAGE(PG8_SB(1, 1), b3 + hstep, voffB); PG8_STAGE(PG8_SA(1, 0), a3, voffA);
;             PG8_WAIT_V(8); PG8_WAIT_L(0); PG8_BAR; PG8_MMA(1, 0, At, B0); PG8_MMA(1, 1, At, B1); PG8_BAR; PG8_SCHED;
	s_add_i32 s43, 0, 0x18000
	s_add_i32 s75, 0, 0x1c000
	v_add_u32_e32 v142, s43, v199
	v_add_u32_e32 v206, s75, v199
	ds_read_b128 v[130:133], v142
	ds_read_b128 v[134:137], v142 offset:1024
	ds_read_b128 v[138:141], v142 offset:2048
	ds_read_b128 v[142:145], v142 offset:3072
	ds_read_b128 v[170:173], v206
	ds_read_b128 v[174:177], v206 offset:1024
	ds_read_b128 v[202:205], v206 offset:2048
	ds_read_b128 v[206:209], v206 offset:3072
	s_add_u32 s14, s14, s84
	s_addc_u32 s15, s15, 0
	s_mov_b32 m0, s83
	v_lshl_add_u64 v[252:253], s[14:15], 0, v[158:159]
	ds_read_b128 v[210:213], v201 offset:32768
	ds_read_b128 v[214:217], v201 offset:33792
	ds_read_b128 v[218:221], v201 offset:34816
	ds_read_b128 v[222:225], v201 offset:35840
	ds_read_b128 v[226:229], v201 offset:36864
	ds_read_b128 v[230:233], v201 offset:37888
	ds_read_b128 v[234:237], v201 offset:38912
	ds_read_b128 v[238:241], v201 offset:39936
	global_load_lds_dwordx4 v[252:253], off
	v_lshl_add_u64 v[252:253], s[14:15], 0, v[160:161]
	s_mov_b32 m0, s24
	s_nop 0
	global_load_lds_dwordx4 v[252:253], off
	s_waitcnt vmcnt(8)
	s_waitcnt lgkmcnt(0)
	s_barrier
	s_setprio 1
	v_mfma_f32_16x16x32_bf16 v[126:129], v[130:133], v[210:213], v[126:129]
	v_mfma_f32_16x16x32_bf16 v[126:129], v[134:137], v[214:217], v[126:129]
	v_mfma_f32_16x16x32_bf16 v[122:125], v[138:141], v[210:213], v[122:125]
	v_mfma_f32_16x16x32_bf16 v[122:125], v[142:145], v[214:217], v[122:125]
	v_mfma_f32_16x16x32_bf16 v[110:113], v[130:133], v[218:221], v[110:113]
	v_mfma_f32_16x16x32_bf16 v[110:113], v[134:137], v[222:225], v[110:113]
	v_mfma_f32_16x16x32_bf16 v[106:109], v[138:141], v[218:221], v[106:109]
	v_mfma_f32_16x16x32_bf16 v[106:109], v[142:145], v[222:225], v[106:109]
	v_mfma_f32_16x16x32_bf16 v[94:97], v[130:133], v[226:229], v[94:97]
	v_mfma_f32_16x16x32_bf16 v[94:97], v[134:137], v[230:233], v[94:97]
	v_mfma_f32_16x16x32_bf16 v[90:93], v[138:141], v[226:229], v[90:93]
	v_mfma_f32_16x16x32_bf16 v[90:93], v[142:145], v[230:233], v[90:93]
	v_mfma_f32_16x16x32_bf16 v[78:81], v[130:133], v[234:237], v[78:81]
	v_mfma_f32_16x16x32_bf16 v[78:81], v[134:137], v[238:241], v[78:81]
	v_mfma_f32_16x16x32_bf16 v[74:77], v[138:141], v[234:237], v[74:77]
	v_mfma_f32_16x16x32_bf16 v[74:77], v[142:145], v[238:241], v[74:77]
	v_mfma_f32_16x16x32_bf16 v[118:121], v[170:173], v[210:213], v[118:121]
	v_mfma_f32_16x16x32_bf16 v[118:121], v[174:177], v[214:217], v[118:121]
	v_mfma_f32_16x16x32_bf16 v[114:117], v[202:205], v[210:213], v[114:117]
	v_mfma_f32_16x16x32_bf16 v[114:117], v[206:209], v[214:217], v[114:117]
	v_mfma_f32_16x16x32_bf16 v[102:105], v[170:173], v[218:221], v[102:105]
	v_mfma_f32_16x16x32_bf16 v[102:105], v[174:177], v[222:225], v[102:105]
	v_mfma_f32_16x16x32_bf16 v[98:101], v[202:205], v[218:221], v[98:101]
	v_mfma_f32_16x16x32_bf16 v[98:101], v[206:209], v[222:225], v[98:101]
	v_mfma_f32_16x16x32_bf16 v[86:89], v[170:173], v[226:229], v[86:89]
	v_mfma_f32_16x16x32_bf16 v[86:89], v[174:177], v[230:233], v[86:89]
	v_mfma_f32_16x16x32_bf16 v[82:85], v[202:205], v[226:229], v[82:85]
	v_mfma_f32_16x16x32_bf16 v[82:85], v[206:209], v[230:233], v[82:85]
	v_mfma_f32_16x16x32_bf16 v[70:73], v[170:173], v[234:237], v[70:73]
	v_mfma_f32_16x16x32_bf16 v[70:73], v[174:177], v[238:241], v[70:73]
	v_mfma_f32_16x16x32_bf16 v[66:69], v[202:205], v[234:237], v[66:69]
	v_mfma_f32_16x16x32_bf16 v[66:69], v[206:209], v[238:241], v[66:69]
	s_setprio 0
	s_barrier
	s_add_i32 s14, s43, s23
	v_lshl_add_u64 v[178:179], v[178:179], 0, s[94:95]
	s_mov_b32 m0, s14
	ds_read_b128 v[210:213], v201 offset:49152
	ds_read_b128 v[214:217], v201 offset:50176
	ds_read_b128 v[218:221], v201 offset:51200
	ds_read_b128 v[222:225], v201 offset:52224
	ds_read_b128 v[226:229], v201 offset:53248
	ds_read_b128 v[230:233], v201 offset:54272
	ds_read_b128 v[234:237], v201 offset:55296
	ds_read_b128 v[238:241], v201 offset:56320
	global_load_lds_dwordx4 v[178:179], off
	v_lshl_add_u64 v[178:179], v[242:243], 0, s[94:95]
	s_add_i32 m0, s14, 0x2000
	s_add_i32 s14, s75, s23
	global_load_lds_dwordx4 v[178:179], off
	v_lshl_add_u64 v[178:179], v[244:245], 0, s[94:95]
	s_mov_b32 m0, s14
	s_nop 0
	global_load_lds_dwordx4 v[178:179], off
	v_lshl_add_u64 v[178:179], v[246:247], 0, s[94:95]
	s_add_i32 m0, s14, 0x2000
	s_nop 0
	global_load_lds_dwordx4 v[178:179], off
	v_lshl_add_u64 v[178:179], v[248:249], 0, s[94:95]
	s_mov_b32 m0, s63
	s_nop 0
	global_load_lds_dwordx4 v[178:179], off
	v_lshl_add_u64 v[178:179], v[250:251], 0, s[94:95]
	s_mov_b32 m0, s70
	s_nop 0
	global_load_lds_dwordx4 v[178:179], off
	s_waitcnt vmcnt(8)
	s_waitcnt lgkmcnt(0)
	s_barrier
	s_setprio 1
	v_mfma_f32_16x16x32_bf16 v[62:65], v[130:133], v[210:213], v[62:65]
	v_mfma_f32_16x16x32_bf16 v[62:65], v[134:137], v[214:217], v[62:65]
	v_mfma_f32_16x16x32_bf16 v[58:61], v[138:141], v[210:213], v[58:61]
	v_mfma_f32_16x16x32_bf16 v[58:61], v[142:145], v[214:217], v[58:61]
	v_mfma_f32_16x16x32_bf16 v[46:49], v[130:133], v[218:221], v[46:49]
	v_mfma_f32_16x16x32_bf16 v[46:49], v[134:137], v[222:225], v[46:49]
	v_mfma_f32_16x16x32_bf16 v[42:45], v[138:141], v[218:221], v[42:45]
	v_mfma_f32_16x16x32_bf16 v[42:45], v[142:145], v[222:225], v[42:45]
	v_mfma_f32_16x16x32_bf16 v[30:33], v[130:133], v[226:229], v[30:33]
	v_mfma_f32_16x16x32_bf16 v[30:33], v[134:137], v[230:233], v[30:33]
	v_mfma_f32_16x16x32_bf16 v[26:29], v[138:141], v[226:229], v[26:29]
	v_mfma_f32_16x16x32_bf16 v[26:29], v[142:145], v[230:233], v[26:29]
	v_mfma_f32_16x16x32_bf16 v[14:17], v[130:133], v[234:237], v[14:17]
	v_mfma_f32_16x16x32_bf16 v[14:17], v[134:137], v[238:241], v[14:17]
	v_mfma_f32_16x16x32_bf16 v[10:13], v[138:141], v[234:237], v[10:13]
	v_mfma_f32_16x16x32_bf16 v[10:13], v[142:145], v[238:241], v[10:13]
	v_mfma_f32_16x16x32_bf16 v[54:57], v[170:173], v[210:213], v[54:57]
	v_mfma_f32_16x16x32_bf16 v[54:57], v[174:177], v[214:217], v[54:57]
	v_mfma_f32_16x16x32_bf16 v[50:53], v[202:205], v[210:213], v[50:53]
	v_mfma_f32_16x16x32_bf16 v[50:53], v[206:209], v[214:217], v[50:53]
	v_mfma_f32_16x16x32_bf16 v[38:41], v[170:173], v[218:221], v[38:41]
	v_mfma_f32_16x16x32_bf16 v[38:41], v[174:177], v[222:225], v[38:41]
	v_mfma_f32_16x16x32_bf16 v[34:37], v[202:205], v[218:221], v[34:37]
	v_mfma_f32_16x16x32_bf16 v[34:37], v[206:209], v[222:225], v[34:37]
	v_mfma_f32_16x16x32_bf16 v[22:25], v[170:173], v[226:229], v[22:25]
	v_mfma_f32_16x16x32_bf16 v[22:25], v[174:177], v[230:233], v[22:25]
	v_mfma_f32_16x16x32_bf16 v[18:21], v[202:205], v[226:229], v[18:21]
	v_mfma_f32_16x16x32_bf16 v[18:21], v[206:209], v[230:233], v[18:21]
	v_mfma_f32_16x16x32_bf16 v[6:9], v[170:173], v[234:237], v[6:9]
	v_mfma_f32_16x16x32_bf16 v[6:9], v[174:177], v[238:241], v[6:9]
	v_mfma_f32_16x16x32_bf16 v[2:5], v[202:205], v[234:237], v[2:5]
	v_mfma_f32_16x16x32_bf16 v[2:5], v[206:209], v[238:241], v[2:5]
	s_setprio 0
	s_barrier
	s_add_u32 s12, s12, 0x100
	s_addc_u32 s13, s13, 0
	s_add_u32 s16, s16, 0x100
	s_addc_u32 s17, s17, 0
	s_cmp_ge_u32 s42, s28
	s_mov_b32 s14, s42
	s_cbranch_scc0 .LBB0_322
